# attention mode 0: nt hint on the opart/lse partial stores (read once next phase) to keep q/k/v cached
# baseline (speedup 1.0000x reference)
; #define LAS __attribute__((address_space(3)))
; __device__ __forceinline__ void attn_phase(const Params& p, LAS unsigned char* lds, int l, int mode) {
;     ...
;             f32x4 sacc[10];
; #pragma unroll
;             for (int i = 0; i < 10; ++i) {
;                 sacc[i] = (f32x4){0.f, 0.f, 0.f, 0.f};
;                 const int kb = kb0 + i, koff = (kb < 8) ? koffP + kb * (16 * 272) : koffC + (kb - 8) * (16 * 272);
; #pragma unroll
;                 for (int s = 0; s < 4; ++s) {
;                     const bf16x8 kf = *(const LAS bf16x8*)(Kl + koff + li * 272 + (32 * s + 8 * g) * 2);
;                     sacc[i] = __builtin_amdgcn_mfma_f32_16x16x32_bf16(kf, qc[s], sacc[i], 0, 0, 0);
;                 }
;             }
.LBB0_311:
	s_xor_b32 s26, s39, 1
	s_lshl_b32 s27, s37, 7
	s_mul_i32 s37, s26, 0x8800
	s_add_i32 s38, s38, 0xffff7800
	v_mov_b32_e32 v119, s38
	v_mov_b32_e32 v179, s37
	v_cndmask_b32_e64 v52, v119, v179, s[4:5]
	v_add_u32_e32 v60, v114, v52
	ds_read_b128 v[52:55], v60
	ds_read_b128 v[56:59], v60 offset:64
	v_cndmask_b32_e64 v174, v119, v179, s[14:15]
	v_add_u32_e32 v178, s27, v102
	s_sub_i32 s27, 0x7f, s27
	v_cmp_lt_i32_e32 vcc, s27, v129
	s_waitcnt lgkmcnt(0)
	v_mfma_f32_16x16x32_bf16 v[52:55], v[52:55], v[48:51], 0
	s_and_b64 vcc, s[2:3], vcc
	v_readlane_b32 s0, v254, 45
	v_readlane_b32 s1, v254, 46
	v_mfma_f32_16x16x32_bf16 v[52:55], v[56:59], v[84:87], v[52:55]
	ds_read_b128 v[56:59], v60 offset:128
	s_mul_i32 s26, s26, 0x9000
	s_add_i32 s13, s13, 0xffff7000
	s_waitcnt lgkmcnt(0)
	v_mfma_f32_16x16x32_bf16 v[52:55], v[56:59], v[88:91], v[52:55]
	ds_read_b128 v[56:59], v60 offset:192
	s_waitcnt lgkmcnt(0)
	v_mfma_f32_16x16x32_bf16 v[96:99], v[56:59], v[92:95], v[52:55]
	s_nop 4
	v_cndmask_b32_e64 v52, v119, v179, s[42:43]
	v_add_u32_e32 v60, v116, v52
	ds_read_b128 v[52:55], v60
	ds_read_b128 v[56:59], v60 offset:64
	s_waitcnt lgkmcnt(1)
	v_mfma_f32_16x16x32_bf16 v[52:55], v[52:55], v[48:51], 0
	s_waitcnt lgkmcnt(0)
	v_mfma_f32_16x16x32_bf16 v[52:55], v[56:59], v[84:87], v[52:55]
	ds_read_b128 v[56:59], v60 offset:128
	s_waitcnt lgkmcnt(0)
	v_mfma_f32_16x16x32_bf16 v[52:55], v[56:59], v[88:91], v[52:55]
	ds_read_b128 v[56:59], v60 offset:192
	s_waitcnt lgkmcnt(0)
	v_mfma_f32_16x16x32_bf16 v[80:83], v[56:59], v[92:95], v[52:55]
	s_nop 4
	v_cndmask_b32_e64 v52, v119, v179, s[6:7]
	v_add_u32_e32 v60, v115, v52
	ds_read_b128 v[52:55], v60
	ds_read_b128 v[56:59], v60 offset:64
	s_waitcnt lgkmcnt(1)
	v_mfma_f32_16x16x32_bf16 v[52:55], v[52:55], v[48:51], 0
	s_waitcnt lgkmcnt(0)
	v_mfma_f32_16x16x32_bf16 v[52:55], v[56:59], v[84:87], v[52:55]
	ds_read_b128 v[56:59], v60 offset:128
	s_waitcnt lgkmcnt(0)
	v_mfma_f32_16x16x32_bf16 v[52:55], v[56:59], v[88:91], v[52:55]
	ds_read_b128 v[56:59], v60 offset:192
	s_waitcnt lgkmcnt(0)
	v_mfma_f32_16x16x32_bf16 v[76:79], v[56:59], v[92:95], v[52:55]
	s_nop 4
	v_cndmask_b32_e64 v52, v119, v179, s[44:45]
	v_add_u32_e32 v60, v117, v52
	ds_read_b128 v[52:55], v60
	ds_read_b128 v[56:59], v60 offset:64
	s_waitcnt lgkmcnt(1)
	v_mfma_f32_16x16x32_bf16 v[52:55], v[52:55], v[48:51], 0
	s_waitcnt lgkmcnt(0)
	v_mfma_f32_16x16x32_bf16 v[52:55], v[56:59], v[84:87], v[52:55]
	ds_read_b128 v[56:59], v60 offset:128
	s_waitcnt lgkmcnt(0)
	v_mfma_f32_16x16x32_bf16 v[52:55], v[56:59], v[88:91], v[52:55]
	ds_read_b128 v[56:59], v60 offset:192
	s_waitcnt lgkmcnt(0)
	v_mfma_f32_16x16x32_bf16 v[72:75], v[56:59], v[92:95], v[52:55]
	s_nop 4
	v_cndmask_b32_e64 v52, v119, v179, s[10:11]
	v_add_u32_e32 v60, v163, v52
	ds_read_b128 v[52:55], v60
	ds_read_b128 v[56:59], v60 offset:64
	s_waitcnt lgkmcnt(1)
	v_mfma_f32_16x16x32_bf16 v[52:55], v[52:55], v[48:51], 0
	s_waitcnt lgkmcnt(0)
	v_mfma_f32_16x16x32_bf16 v[52:55], v[56:59], v[84:87], v[52:55]
	ds_read_b128 v[56:59], v60 offset:128
	s_waitcnt lgkmcnt(0)
	v_mfma_f32_16x16x32_bf16 v[52:55], v[56:59], v[88:91], v[52:55]
	ds_read_b128 v[56:59], v60 offset:192
	s_waitcnt lgkmcnt(0)
	v_mfma_f32_16x16x32_bf16 v[68:71], v[56:59], v[92:95], v[52:55]
	s_nop 4
	v_cndmask_b32_e64 v52, v119, v179, s[46:47]
	v_add_u32_e32 v60, v164, v52
	ds_read_b128 v[52:55], v60
	ds_read_b128 v[56:59], v60 offset:64
	s_waitcnt lgkmcnt(1)
	v_mfma_f32_16x16x32_bf16 v[52:55], v[52:55], v[48:51], 0
	s_waitcnt lgkmcnt(0)
	v_mfma_f32_16x16x32_bf16 v[52:55], v[56:59], v[84:87], v[52:55]
	ds_read_b128 v[56:59], v60 offset:128
	s_waitcnt lgkmcnt(0)
	v_mfma_f32_16x16x32_bf16 v[52:55], v[56:59], v[88:91], v[52:55]
	ds_read_b128 v[56:59], v60 offset:192
	v_add_u32_e32 v60, v165, v174
	v_add_u32_e32 v174, v166, v174
	s_waitcnt lgkmcnt(0)
	v_mfma_f32_16x16x32_bf16 v[64:67], v[56:59], v[92:95], v[52:55]
	s_nop 2
	ds_read_b128 v[52:55], v60
	ds_read_b128 v[56:59], v60 offset:64
	s_waitcnt lgkmcnt(1)
	v_mfma_f32_16x16x32_bf16 v[52:55], v[52:55], v[48:51], 0
	s_waitcnt lgkmcnt(0)
	v_mfma_f32_16x16x32_bf16 v[52:55], v[56:59], v[84:87], v[52:55]
	ds_read_b128 v[56:59], v60 offset:128
	s_waitcnt lgkmcnt(0)
	v_mfma_f32_16x16x32_bf16 v[52:55], v[56:59], v[88:91], v[52:55]
	ds_read_b128 v[56:59], v60 offset:192
	s_waitcnt lgkmcnt(0)
	v_mfma_f32_16x16x32_bf16 v[60:63], v[56:59], v[92:95], v[52:55]
	s_nop 4
	ds_read_b128 v[52:55], v174
	ds_read_b128 v[56:59], v174 offset:64
	s_waitcnt lgkmcnt(1)
	v_mfma_f32_16x16x32_bf16 v[52:55], v[52:55], v[48:51], 0
	s_waitcnt lgkmcnt(0)
	v_mfma_f32_16x16x32_bf16 v[52:55], v[56:59], v[84:87], v[52:55]
	ds_read_b128 v[56:59], v174 offset:128
	s_waitcnt lgkmcnt(0)
	v_mfma_f32_16x16x32_bf16 v[52:55], v[56:59], v[88:91], v[52:55]
	ds_read_b128 v[56:59], v174 offset:192
	s_waitcnt lgkmcnt(0)
	v_mfma_f32_16x16x32_bf16 v[56:59], v[56:59], v[92:95], v[52:55]
	s_nop 4
	v_cndmask_b32_e64 v52, v119, v179, s[16:17]
	v_add_u32_e32 v180, v167, v52
	ds_read_b128 v[52:55], v180
	ds_read_b128 v[174:177], v180 offset:64
	s_waitcnt lgkmcnt(1)
	v_mfma_f32_16x16x32_bf16 v[52:55], v[52:55], v[48:51], 0
	v_cndmask_b32_e64 v119, v119, v179, s[48:49]
	v_add_u32_e32 v119, v168, v119
	v_ashrrev_i32_e32 v179, 31, v178
	s_waitcnt lgkmcnt(0)
	v_mfma_f32_16x16x32_bf16 v[52:55], v[174:177], v[84:87], v[52:55]
	ds_read_b128 v[174:177], v180 offset:128
	s_waitcnt lgkmcnt(0)
	v_mfma_f32_16x16x32_bf16 v[52:55], v[174:177], v[88:91], v[52:55]
	ds_read_b128 v[174:177], v180 offset:192
	s_waitcnt lgkmcnt(0)
	v_mfma_f32_16x16x32_bf16 v[52:55], v[174:177], v[92:95], v[52:55]
	ds_read_b128 v[174:177], v119
	s_waitcnt lgkmcnt(0)
; #define LAS __attribute__((address_space(3)))
; __device__ __forceinline__ void attn_phase(const Params& p, LAS unsigned char* lds, int l, int mode) {
;     ...
;             for (int i = 0; i < 10; ++i) {
;                 sacc[i] = (f32x4){0.f, 0.f, 0.f, 0.f};
;                 const int kb = kb0 + i, koff = (kb < 8) ? koffP + kb * (16 * 272) : koffC + (kb - 8) * (16 * 272);
; #pragma unroll
;                 for (int s = 0; s < 4; ++s) {
;                     const bf16x8 kf = *(const LAS bf16x8*)(Kl + koff + li * 272 + (32 * s + 8 * g) * 2);
;                     sacc[i] = __builtin_amdgcn_mfma_f32_16x16x32_bf16(kf, qc[s], sacc[i], 0, 0, 0);
;                 }
;             }
;             float mx = -1e30f;
; #pragma unroll
;             for (int i = 0; i < 10; ++i)
; #pragma unroll
;                 for (int j = 0; j < 4; ++j) {
;                     const int kj = 16 * (kb0 + i) + 4 * g + j, dist = 128 + qi - kj;
;                     const bool valid = (dist >= 0) && (dist <= 128) && (mbase + kj >= 0);
;                     const float sv = valid ? sacc[i][j] : -1e30f;
;                     sacc[i][j] = sv; mx = fmaxf(mx, sv);
;                 }
;             mx = fmaxf(mx, __shfl_xor(mx, 16)); mx = fmaxf(mx, __shfl_xor(mx, 32));
	v_mfma_f32_16x16x32_bf16 v[48:51], v[174:177], v[48:51], 0
	ds_read_b128 v[174:177], v119 offset:64
	s_waitcnt lgkmcnt(0)
	v_mfma_f32_16x16x32_bf16 v[48:51], v[174:177], v[84:87], v[48:51]
	ds_read_b128 v[84:87], v119 offset:128
	s_waitcnt lgkmcnt(0)
	v_mfma_f32_16x16x32_bf16 v[48:51], v[84:87], v[88:91], v[48:51]
	ds_read_b128 v[84:87], v119 offset:192
	s_waitcnt lgkmcnt(0)
	v_mfma_f32_16x16x32_bf16 v[48:51], v[84:87], v[92:95], v[48:51]
	v_cndmask_b32_e32 v86, v225, v96, vcc
	v_cmp_le_i32_e32 vcc, s27, v129
	s_and_b64 vcc, s[50:51], vcc
	v_lshlrev_b64 v[84:85], s30, v[178:179]
	v_cndmask_b32_e32 v87, v225, v97, vcc
	v_cmp_lt_i32_e32 vcc, s27, v130
	s_and_b64 vcc, s[54:55], vcc
	s_mov_b32 s30, 0xf149f2ca
	v_cndmask_b32_e32 v88, v225, v98, vcc
	v_cmp_lt_i32_e32 vcc, s27, v131
	s_and_b64 vcc, s[56:57], vcc
	v_max3_f32 v90, v86, s30, v87
	v_cndmask_b32_e32 v89, v225, v99, vcc
	v_cmp_lt_i32_e32 vcc, s27, v132
	s_and_b64 vcc, s[58:59], vcc
	v_max3_f32 v91, v90, v88, v89
	v_cndmask_b32_e32 v80, v225, v80, vcc
	v_cmp_le_i32_e32 vcc, s27, v132
	s_and_b64 vcc, s[60:61], vcc
	v_and_b32_e32 v92, 64, v223
	v_cndmask_b32_e32 v90, v225, v81, vcc
	v_cmp_lt_i32_e32 vcc, s27, v133
	s_and_b64 vcc, s[62:63], vcc
	v_max3_f32 v81, v91, v80, v90
	v_cndmask_b32_e32 v82, v225, v82, vcc
	v_cmp_lt_i32_e32 vcc, s27, v134
	s_and_b64 vcc, s[64:65], vcc
	v_xor_b32_e32 v91, 16, v223
	v_cndmask_b32_e32 v83, v225, v83, vcc
	v_cmp_lt_i32_e32 vcc, s27, v135
	s_and_b64 vcc, s[66:67], vcc
	v_max3_f32 v81, v81, v82, v83
	v_cndmask_b32_e32 v76, v225, v76, vcc
	v_cmp_le_i32_e32 vcc, s27, v135
	s_and_b64 vcc, s[68:69], vcc
	v_add_u32_e32 v92, 64, v92
	v_cndmask_b32_e32 v77, v225, v77, vcc
	v_cmp_lt_i32_e32 vcc, s27, v136
	s_and_b64 vcc, s[70:71], vcc
	v_max3_f32 v81, v81, v76, v77
	v_cndmask_b32_e32 v78, v225, v78, vcc
	v_cmp_lt_i32_e32 vcc, s27, v137
	s_and_b64 vcc, s[72:73], vcc
	s_nop 0
	v_cndmask_b32_e32 v79, v225, v79, vcc
	v_cmp_lt_i32_e32 vcc, s27, v138
	s_and_b64 vcc, s[74:75], vcc
	v_max3_f32 v81, v81, v78, v79
	v_cndmask_b32_e32 v72, v225, v72, vcc
	v_cmp_le_i32_e32 vcc, s27, v138
	s_and_b64 vcc, s[76:77], vcc
	s_nop 0
	v_cndmask_b32_e32 v73, v225, v73, vcc
	v_cmp_lt_i32_e32 vcc, s27, v139
	s_and_b64 vcc, s[78:79], vcc
	v_max3_f32 v81, v81, v72, v73
	v_cndmask_b32_e32 v74, v225, v74, vcc
	v_cmp_lt_i32_e32 vcc, s27, v140
	s_and_b64 vcc, s[80:81], vcc
	s_nop 0
	v_cndmask_b32_e32 v75, v225, v75, vcc
	v_cmp_lt_i32_e32 vcc, s27, v141
	s_and_b64 vcc, s[82:83], vcc
	v_max3_f32 v81, v81, v74, v75
	v_cndmask_b32_e32 v68, v225, v68, vcc
	v_cmp_le_i32_e32 vcc, s27, v141
	s_and_b64 vcc, s[84:85], vcc
	s_nop 0
	v_cndmask_b32_e32 v69, v225, v69, vcc
	v_cmp_lt_i32_e32 vcc, s27, v142
	s_and_b64 vcc, s[88:89], vcc
	v_max3_f32 v81, v81, v68, v69
	v_cndmask_b32_e32 v70, v225, v70, vcc
	v_cmp_lt_i32_e32 vcc, s27, v143
	s_and_b64 vcc, s[90:91], vcc
	s_nop 0
	v_cndmask_b32_e32 v71, v225, v71, vcc
	v_cmp_lt_i32_e32 vcc, s27, v144
	s_and_b64 vcc, s[92:93], vcc
	v_max3_f32 v81, v81, v70, v71
	v_cndmask_b32_e32 v64, v225, v64, vcc
	v_cmp_le_i32_e32 vcc, s27, v144
	s_and_b64 vcc, s[94:95], vcc
	s_nop 0
	v_cndmask_b32_e32 v65, v225, v65, vcc
	v_cmp_lt_i32_e32 vcc, s27, v145
	s_and_b64 vcc, s[96:97], vcc
	v_max3_f32 v81, v81, v64, v65
	v_cndmask_b32_e32 v66, v225, v66, vcc
	v_cmp_lt_i32_e32 vcc, s27, v146
	s_and_b64 vcc, s[98:99], vcc
	s_nop 0
	v_cndmask_b32_e32 v67, v225, v67, vcc
	v_cmp_lt_i32_e32 vcc, s27, v147
	s_and_b64 vcc, s[0:1], vcc
	v_readlane_b32 s0, v254, 47
	v_cndmask_b32_e32 v60, v225, v60, vcc
	v_cmp_le_i32_e32 vcc, s27, v147
	v_readlane_b32 s1, v254, 48
	s_and_b64 vcc, s[0:1], vcc
	v_readlane_b32 s0, v254, 49
	v_cndmask_b32_e32 v61, v225, v61, vcc
	v_cmp_lt_i32_e32 vcc, s27, v148
	v_readlane_b32 s1, v254, 50
	s_and_b64 vcc, s[0:1], vcc
	v_readlane_b32 s0, v254, 51
	v_cndmask_b32_e32 v62, v225, v62, vcc
	v_cmp_lt_i32_e32 vcc, s27, v149
	v_readlane_b32 s1, v254, 52
	s_and_b64 vcc, s[0:1], vcc
	v_readlane_b32 s0, v254, 53
	v_cndmask_b32_e32 v63, v225, v63, vcc
	v_cmp_lt_i32_e32 vcc, s27, v150
	v_readlane_b32 s1, v254, 54
	s_and_b64 vcc, s[0:1], vcc
	v_readlane_b32 s0, v254, 55
	v_cndmask_b32_e32 v56, v225, v56, vcc
	v_cmp_le_i32_e32 vcc, s27, v150
	v_readlane_b32 s1, v254, 56
	s_and_b64 vcc, s[0:1], vcc
	v_readlane_b32 s0, v254, 57
	v_cndmask_b32_e32 v57, v225, v57, vcc
	v_cmp_lt_i32_e32 vcc, s27, v151
	v_readlane_b32 s1, v254, 58
	s_and_b64 vcc, s[0:1], vcc
	v_readlane_b32 s0, v254, 59
	v_cndmask_b32_e32 v58, v225, v58, vcc
	v_cmp_lt_i32_e32 vcc, s27, v156
	v_readlane_b32 s1, v254, 60
	s_and_b64 vcc, s[0:1], vcc
	v_readlane_b32 s0, v254, 41
	v_cndmask_b32_e32 v59, v225, v59, vcc
	v_cmp_lt_i32_e32 vcc, s27, v157
	v_readlane_b32 s1, v254, 42
	s_and_b64 vcc, s[0:1], vcc
	v_readlane_b32 s0, v254, 36
	v_cndmask_b32_e32 v52, v225, v52, vcc
	v_cmp_le_i32_e32 vcc, s27, v157
	v_readlane_b32 s1, v254, 37
	s_and_b64 vcc, s[0:1], vcc
	v_readlane_b32 s0, v254, 43
	v_cndmask_b32_e32 v53, v225, v53, vcc
	v_cmp_lt_i32_e32 vcc, s27, v158
	v_readlane_b32 s1, v254, 44
	s_and_b64 vcc, s[0:1], vcc
	v_readlane_b32 s0, v254, 39
	v_cndmask_b32_e32 v54, v225, v54, vcc
	v_cmp_lt_i32_e32 vcc, s27, v159
	v_readlane_b32 s1, v254, 40
	s_and_b64 vcc, s[0:1], vcc
	v_readlane_b32 s0, v254, 61
	v_cndmask_b32_e32 v55, v225, v55, vcc
	v_cmp_lt_i32_e32 vcc, s27, v160
	v_readlane_b32 s1, v254, 62
	s_and_b64 vcc, s[0:1], vcc
	v_readlane_b32 s0, v254, 63
	v_max3_f32 v81, v81, v66, v67
	v_cndmask_b32_e32 v48, v225, v48, vcc
	v_cmp_le_i32_e32 vcc, s27, v160
	v_readlane_b32 s1, v255, 0
	v_max3_f32 v81, v81, v60, v61
	s_and_b64 vcc, s[0:1], vcc
	v_readlane_b32 s0, v255, 1
	v_max3_f32 v81, v81, v62, v63
	v_cndmask_b32_e32 v49, v225, v49, vcc
	v_cmp_lt_i32_e32 vcc, s27, v161
	v_readlane_b32 s1, v255, 2
	v_max3_f32 v81, v81, v56, v57
	s_and_b64 vcc, s[0:1], vcc
	v_readlane_b32 s0, v255, 3
	v_max3_f32 v81, v81, v58, v59
	v_cndmask_b32_e32 v50, v225, v50, vcc
	v_cmp_lt_i32_e32 vcc, s27, v162
	v_readlane_b32 s1, v255, 4
	v_max3_f32 v81, v81, v52, v53
	s_and_b64 vcc, s[0:1], vcc
	v_max3_f32 v81, v81, v54, v55
	v_cndmask_b32_e32 v51, v225, v51, vcc
	v_cmp_lt_i32_e32 vcc, v91, v92
	v_max3_f32 v81, v81, v48, v49
	v_max3_f32 v81, v81, v50, v51
	v_cndmask_b32_e32 v91, v223, v91, vcc
	v_lshlrev_b32_e32 v91, 2, v91
	ds_bpermute_b32 v93, v91, v81
	s_waitcnt lgkmcnt(0)
; #define LAS __attribute__((address_space(3)))
; __device__ __forceinline__ void attn_phase(const Params& p, LAS unsigned char* lds, int l, int mode) {
;     ...
;             mx = fmaxf(mx, __shfl_xor(mx, 16)); mx = fmaxf(mx, __shfl_xor(mx, 32));
;             float lsum = 0.f;
; #pragma unroll
;             for (int i = 0; i < 10; ++i)
; #pragma unroll
;                 for (int j = 0; j < 4; ++j) { const float pv = __builtin_amdgcn_exp2f(sacc[i][j] - mx); sacc[i][j] = pv; lsum += pv; }
;             lsum += __shfl_xor(lsum, 16); lsum += __shfl_xor(lsum, 32);
;             u32x2 x1[8], x2[8]; float l1 = 0.f, l2 = 0.f;
;             if (mode) {
;                 l1 = lse[qtok * 8 + h]; l2 = lse[((size_t)T_TOK + qtok) * 8 + h];
;                 const bf16_t* p1 = opart + qtok * 1024 + h * 128 + 4 * g; const bf16_t* p2 = p1 + (size_t)T_TOK * 1024;
; #pragma unroll
;                 for (int db = 0; db < 8; ++db) { x1[db] = *(const u32x2*)(p1 + 16 * db); x2[db] = *(const u32x2*)(p2 + 16 * db); }
;             }
;             f32x4 oacc[8];
; #pragma unroll
;             for (int db = 0; db < 8; ++db) oacc[db] = (f32x4){0.f, 0.f, 0.f, 0.f};
;             const int vlane = (4 * g + (li >> 2)) * 288 + (4 * (li & 3)) * 2;
; #pragma unroll
;             for (int t = 0; t < 5; ++t) {
;                 u32x4 pw; pw.x = cvt_pk_bf16(sacc[2 * t][0], sacc[2 * t][1]); pw.y = cvt_pk_bf16(sacc[2 * t][2], sacc[2 * t][3]);
;                 pw.z = cvt_pk_bf16(sacc[2 * t + 1][0], sacc[2 * t + 1][1]); pw.w = cvt_pk_bf16(sacc[2 * t + 1][2], sacc[2 * t + 1][3]);
;                 const bf16x8 pf = __builtin_bit_cast(bf16x8, pw);
;                 const int kbv = kb0 + 2 * t, voff = (kbv < 8) ? voffP + kbv * (16 * 288) : voffC + (kbv - 8) * (16 * 288);
;                 const LAS unsigned char* vb = Vl + voff + vlane;
; #pragma unroll
;                 for (int db = 0; db < 8; ++db) {
;                     const s16x4 lo = __builtin_bit_cast(s16x4, __builtin_amdgcn_ds_read_tr16_b64_v4i16((LAS s16x4*)(vb + db * 32)));
;                     const s16x4 hi = __builtin_bit_cast(s16x4, __builtin_amdgcn_ds_read_tr16_b64_v4i16((LAS s16x4*)(vb + 16 * 288 + db * 32)));
;                     const bf16x8 vf = __builtin_shufflevector(lo, hi, 0, 1, 2, 3, 4, 5, 6, 7);
;                     oacc[db] = __builtin_amdgcn_mfma_f32_16x16x32_bf16(vf, pf, oacc[db], 0, 0, 0);
	v_max_f32_e32 v93, v93, v93
	v_max_f32_e32 v81, v81, v93
	v_xor_b32_e32 v93, 32, v223
	v_cmp_lt_i32_e32 vcc, v93, v92
	s_nop 1
	v_cndmask_b32_e32 v92, v223, v93, vcc
	v_lshlrev_b32_e32 v92, 2, v92
	ds_bpermute_b32 v93, v92, v81
	s_waitcnt lgkmcnt(0)
	v_max_f32_e32 v93, v93, v93
	v_max_f32_e32 v81, v81, v93
	v_sub_f32_e32 v86, v86, v81
	v_exp_f32_e32 v93, v86
	v_sub_f32_e32 v87, v87, v81
	v_exp_f32_e32 v94, v87
	v_sub_f32_e32 v87, v88, v81
	v_exp_f32_e32 v88, v87
	v_sub_f32_e32 v87, v89, v81
	v_exp_f32_e32 v89, v87
	v_sub_f32_e32 v80, v80, v81
	v_add_f32_e32 v86, 0, v93
	v_exp_f32_e32 v95, v80
	v_add_f32_e32 v86, v94, v86
	v_add_f32_e32 v86, v88, v86
	v_add_f32_e32 v86, v89, v86
	v_add_f32_e32 v80, v95, v86
	v_sub_f32_e32 v86, v90, v81
	v_exp_f32_e32 v90, v86
	v_sub_f32_e32 v82, v82, v81
	v_exp_f32_e32 v96, v82
	v_sub_f32_e32 v82, v83, v81
	v_exp_f32_e32 v97, v82
	v_sub_f32_e32 v76, v76, v81
	v_exp_f32_e32 v76, v76
	v_sub_f32_e32 v77, v77, v81
	v_add_f32_e32 v80, v90, v80
	v_exp_f32_e32 v77, v77
	v_sub_f32_e32 v78, v78, v81
	v_add_f32_e32 v80, v96, v80
	v_exp_f32_e32 v78, v78
	v_sub_f32_e32 v79, v79, v81
	v_add_f32_e32 v80, v97, v80
	v_exp_f32_e32 v79, v79
	v_add_f32_e32 v80, v76, v80
	v_add_f32_e32 v80, v77, v80
	v_add_f32_e32 v80, v78, v80
	v_sub_f32_e32 v72, v72, v81
	v_add_f32_e32 v82, v79, v80
	v_exp_f32_e32 v80, v72
	v_sub_f32_e32 v73, v73, v81
	v_sub_f32_e32 v68, v68, v81
	v_exp_f32_e32 v68, v68
	v_add_f32_e32 v72, v80, v82
	v_exp_f32_e32 v82, v73
	v_sub_f32_e32 v73, v74, v81
	v_exp_f32_e32 v83, v73
	v_sub_f32_e32 v73, v75, v81
	v_exp_f32_e32 v87, v73
	v_sub_f32_e32 v69, v69, v81
	v_add_f32_e32 v72, v82, v72
	v_exp_f32_e32 v69, v69
	v_sub_f32_e32 v70, v70, v81
	v_add_f32_e32 v72, v83, v72
	v_exp_f32_e32 v70, v70
	v_sub_f32_e32 v71, v71, v81
	v_add_f32_e32 v72, v87, v72
	v_exp_f32_e32 v71, v71
	v_add_f32_e32 v72, v68, v72
	v_add_f32_e32 v72, v69, v72
	v_add_f32_e32 v72, v70, v72
	v_sub_f32_e32 v64, v64, v81
	v_add_f32_e32 v73, v71, v72
	v_exp_f32_e32 v72, v64
	v_sub_f32_e32 v65, v65, v81
	v_sub_f32_e32 v60, v60, v81
	v_exp_f32_e32 v60, v60
	v_add_f32_e32 v64, v72, v73
	v_exp_f32_e32 v73, v65
	v_sub_f32_e32 v65, v66, v81
	v_exp_f32_e32 v74, v65
	v_sub_f32_e32 v65, v67, v81
	v_exp_f32_e32 v75, v65
	v_sub_f32_e32 v61, v61, v81
	v_add_f32_e32 v64, v73, v64
	v_exp_f32_e32 v61, v61
	v_sub_f32_e32 v62, v62, v81
	v_add_f32_e32 v64, v74, v64
	v_exp_f32_e32 v62, v62
	v_sub_f32_e32 v63, v63, v81
	v_add_f32_e32 v64, v75, v64
	v_exp_f32_e32 v63, v63
	v_add_f32_e32 v64, v60, v64
	v_add_f32_e32 v64, v61, v64
	v_add_f32_e32 v64, v62, v64
	v_sub_f32_e32 v56, v56, v81
	v_add_f32_e32 v65, v63, v64
	v_exp_f32_e32 v64, v56
	v_sub_f32_e32 v57, v57, v81
	v_sub_f32_e32 v52, v52, v81
	v_exp_f32_e32 v52, v52
	v_add_f32_e32 v56, v64, v65
	v_exp_f32_e32 v65, v57
	v_sub_f32_e32 v57, v58, v81
	v_exp_f32_e32 v66, v57
	v_sub_f32_e32 v57, v59, v81
	v_exp_f32_e32 v67, v57
	v_sub_f32_e32 v53, v53, v81
	v_add_f32_e32 v56, v65, v56
	v_exp_f32_e32 v53, v53
	v_sub_f32_e32 v54, v54, v81
	v_add_f32_e32 v56, v66, v56
	v_exp_f32_e32 v54, v54
	v_sub_f32_e32 v55, v55, v81
	v_add_f32_e32 v56, v67, v56
	v_exp_f32_e32 v55, v55
	v_add_f32_e32 v56, v52, v56
	v_add_f32_e32 v56, v53, v56
	v_add_f32_e32 v56, v54, v56
	v_sub_f32_e32 v48, v48, v81
	v_add_f32_e32 v57, v55, v56
	v_exp_f32_e32 v56, v48
	v_sub_f32_e32 v49, v49, v81
	v_add_f32_e32 v48, v56, v57
	v_exp_f32_e32 v57, v49
	v_sub_f32_e32 v49, v50, v81
	v_exp_f32_e32 v58, v49
	v_sub_f32_e32 v49, v51, v81
	v_exp_f32_e32 v59, v49
	v_add_f32_e32 v48, v57, v48
	v_add_f32_e32 v48, v58, v48
	v_add_f32_e32 v48, v59, v48
	ds_bpermute_b32 v49, v91, v48
	s_waitcnt lgkmcnt(0)
	v_add_f32_e32 v48, v48, v49
	ds_bpermute_b32 v49, v92, v48
	s_waitcnt lgkmcnt(0)
	v_add_f32_e32 v86, v48, v49
	v_cvt_pk_bf16_f32 v48, v93, v94
	v_cvt_pk_bf16_f32 v49, v88, v89
	v_mov_b32_e32 v88, s13
	v_mov_b32_e32 v89, s26
	v_cvt_pk_bf16_f32 v50, v95, v90
	v_cndmask_b32_e64 v90, v88, v89, s[4:5]
	v_add_u32_e32 v98, v169, v90
	v_cvt_pk_bf16_f32 v51, v96, v97
	ds_read_b64_tr_b16 v[92:93], v98 offset:4608
	ds_read_b64_tr_b16 v[90:91], v98
	ds_read_b64_tr_b16 v[94:95], v98 offset:32
	ds_read_b64_tr_b16 v[96:97], v98 offset:4640
	ds_read_b64_tr_b16 v[174:175], v98 offset:64
	ds_read_b64_tr_b16 v[176:177], v98 offset:4672
	ds_read_b64_tr_b16 v[178:179], v98 offset:96
	ds_read_b64_tr_b16 v[180:181], v98 offset:4704
	ds_read_b64_tr_b16 v[182:183], v98 offset:128
	ds_read_b64_tr_b16 v[184:185], v98 offset:4736
	ds_read_b64_tr_b16 v[186:187], v98 offset:160
	ds_read_b64_tr_b16 v[188:189], v98 offset:4768
	ds_read_b64_tr_b16 v[190:191], v98 offset:192
	ds_read_b64_tr_b16 v[192:193], v98 offset:4800
	ds_read_b64_tr_b16 v[194:195], v98 offset:224
	ds_read_b64_tr_b16 v[196:197], v98 offset:4832
	v_cvt_pk_bf16_f32 v76, v76, v77
	v_cvt_pk_bf16_f32 v77, v78, v79
	v_cvt_pk_bf16_f32 v78, v80, v82
	v_cndmask_b32_e64 v80, v88, v89, s[6:7]
	v_add_u32_e32 v80, v170, v80
	s_waitcnt lgkmcnt(14)
	v_mfma_f32_16x16x32_bf16 v[90:93], v[90:93], v[48:51], 0
	v_cvt_pk_bf16_f32 v79, v83, v87
	s_add_u32 s13, s18, s35
	s_addc_u32 s18, s19, 0
	s_waitcnt lgkmcnt(12)
	v_mfma_f32_16x16x32_bf16 v[94:97], v[94:97], v[48:51], 0
	s_add_u32 s13, s13, s20
	s_addc_u32 s19, s18, s21
	s_add_u32 s18, s13, 0xffffc000
	s_waitcnt lgkmcnt(10)
	v_mfma_f32_16x16x32_bf16 v[174:177], v[174:177], v[48:51], 0
	s_addc_u32 s19, s19, -1
	s_lshl_b32 s52, s12, 8
	s_waitcnt lgkmcnt(8)
	v_mfma_f32_16x16x32_bf16 v[178:181], v[178:181], v[48:51], 0
	s_waitcnt lgkmcnt(6)
	v_mfma_f32_16x16x32_bf16 v[182:185], v[182:185], v[48:51], 0
	s_waitcnt lgkmcnt(4)
	v_mfma_f32_16x16x32_bf16 v[186:189], v[186:189], v[48:51], 0
	s_waitcnt lgkmcnt(2)
; #define LAS __attribute__((address_space(3)))
; __device__ __forceinline__ unsigned cvt_pk_bf16(float lo, float hi) { unsigned r; asm volatile("v_cvt_pk_bf16_f32 %0, %1, %2" : "=v"(r) : "v"(lo), "v"(hi)); return r; }
; __device__ __forceinline__ void attn_phase(const Params& p, LAS unsigned char* lds, int l, int mode) {
;     ...
; #pragma unroll
;             for (int t = 0; t < 5; ++t) {
;                 u32x4 pw; pw.x = cvt_pk_bf16(sacc[2 * t][0], sacc[2 * t][1]); pw.y = cvt_pk_bf16(sacc[2 * t][2], sacc[2 * t][3]);
;                 pw.z = cvt_pk_bf16(sacc[2 * t + 1][0], sacc[2 * t + 1][1]); pw.w = cvt_pk_bf16(sacc[2 * t + 1][2], sacc[2 * t + 1][3]);
;                 const bf16x8 pf = __builtin_bit_cast(bf16x8, pw);
;                 const int kbv = kb0 + 2 * t, voff = (kbv < 8) ? voffP + kbv * (16 * 288) : voffC + (kbv - 8) * (16 * 288);
;                 const LAS unsigned char* vb = Vl + voff + vlane;
; #pragma unroll
;                 for (int db = 0; db < 8; ++db) {
;                     const s16x4 lo = __builtin_bit_cast(s16x4, __builtin_amdgcn_ds_read_tr16_b64_v4i16((LAS s16x4*)(vb + db * 32)));
;                     const s16x4 hi = __builtin_bit_cast(s16x4, __builtin_amdgcn_ds_read_tr16_b64_v4i16((LAS s16x4*)(vb + 16 * 288 + db * 32)));
;                     const bf16x8 vf = __builtin_shufflevector(lo, hi, 0, 1, 2, 3, 4, 5, 6, 7);
;                     oacc[db] = __builtin_amdgcn_mfma_f32_16x16x32_bf16(vf, pf, oacc[db], 0, 0, 0);
;                 }
;             }
	v_mfma_f32_16x16x32_bf16 v[190:193], v[190:193], v[48:51], 0
	s_waitcnt lgkmcnt(0)
	v_mfma_f32_16x16x32_bf16 v[48:51], v[194:197], v[48:51], 0
	ds_read_b64_tr_b16 v[196:197], v80 offset:4608
	ds_read_b64_tr_b16 v[194:195], v80
	ds_read_b64_tr_b16 v[198:199], v80 offset:32
	ds_read_b64_tr_b16 v[200:201], v80 offset:4640
	s_waitcnt lgkmcnt(2)
	v_mfma_f32_16x16x32_bf16 v[90:93], v[194:197], v[76:79], v[90:93]
	ds_read_b64_tr_b16 v[194:195], v80 offset:64
	ds_read_b64_tr_b16 v[196:197], v80 offset:4672
	s_waitcnt lgkmcnt(0)
	v_mfma_f32_16x16x32_bf16 v[174:177], v[194:197], v[76:79], v[174:177]
	ds_read_b64_tr_b16 v[194:195], v80 offset:96
	ds_read_b64_tr_b16 v[196:197], v80 offset:4704
	s_waitcnt lgkmcnt(0)
	v_mfma_f32_16x16x32_bf16 v[178:181], v[194:197], v[76:79], v[178:181]
	ds_read_b64_tr_b16 v[194:195], v80 offset:128
	ds_read_b64_tr_b16 v[196:197], v80 offset:4736
	s_waitcnt lgkmcnt(0)
	v_mfma_f32_16x16x32_bf16 v[182:185], v[194:197], v[76:79], v[182:185]
	ds_read_b64_tr_b16 v[194:195], v80 offset:160
	ds_read_b64_tr_b16 v[196:197], v80 offset:4768
	s_waitcnt lgkmcnt(0)
	v_mfma_f32_16x16x32_bf16 v[186:189], v[194:197], v[76:79], v[186:189]
	ds_read_b64_tr_b16 v[194:195], v80 offset:192
	ds_read_b64_tr_b16 v[196:197], v80 offset:4800
	s_waitcnt lgkmcnt(0)
	v_mfma_f32_16x16x32_bf16 v[190:193], v[194:197], v[76:79], v[190:193]
	ds_read_b64_tr_b16 v[194:195], v80 offset:224
	ds_read_b64_tr_b16 v[196:197], v80 offset:4832
	v_cvt_pk_bf16_f32 v68, v68, v69
	v_cvt_pk_bf16_f32 v69, v70, v71
	v_cvt_pk_bf16_f32 v70, v72, v73
	v_cndmask_b32_e64 v72, v88, v89, s[10:11]
	v_add_u32_e32 v80, v171, v72
	v_mfma_f32_16x16x32_bf16 v[94:97], v[198:201], v[76:79], v[94:97]
	v_cvt_pk_bf16_f32 v71, v74, v75
	s_waitcnt lgkmcnt(0)
	v_mfma_f32_16x16x32_bf16 v[48:51], v[194:197], v[76:79], v[48:51]
	ds_read_b64_tr_b16 v[74:75], v80 offset:4608
	ds_read_b64_tr_b16 v[72:73], v80
	ds_read_b64_tr_b16 v[76:77], v80 offset:32
	ds_read_b64_tr_b16 v[78:79], v80 offset:4640
	s_waitcnt lgkmcnt(2)
	v_mfma_f32_16x16x32_bf16 v[72:75], v[72:75], v[68:71], v[90:93]
	s_nop 2
	ds_read_b64_tr_b16 v[90:91], v80 offset:64
	ds_read_b64_tr_b16 v[92:93], v80 offset:4672
	s_waitcnt lgkmcnt(2)
	v_mfma_f32_16x16x32_bf16 v[76:79], v[76:79], v[68:71], v[94:97]
	s_nop 2
	ds_read_b64_tr_b16 v[94:95], v80 offset:96
	ds_read_b64_tr_b16 v[96:97], v80 offset:4704
	s_waitcnt lgkmcnt(2)
	v_mfma_f32_16x16x32_bf16 v[90:93], v[90:93], v[68:71], v[174:177]
	s_nop 2
	ds_read_b64_tr_b16 v[174:175], v80 offset:128
	ds_read_b64_tr_b16 v[176:177], v80 offset:4736
	s_waitcnt lgkmcnt(2)
	v_mfma_f32_16x16x32_bf16 v[94:97], v[94:97], v[68:71], v[178:181]
	s_nop 2
	ds_read_b64_tr_b16 v[178:179], v80 offset:160
	ds_read_b64_tr_b16 v[180:181], v80 offset:4768
	s_waitcnt lgkmcnt(2)
	v_mfma_f32_16x16x32_bf16 v[174:177], v[174:177], v[68:71], v[182:185]
	s_nop 2
	ds_read_b64_tr_b16 v[182:183], v80 offset:192
	ds_read_b64_tr_b16 v[184:185], v80 offset:4800
	s_waitcnt lgkmcnt(2)
	v_mfma_f32_16x16x32_bf16 v[178:181], v[178:181], v[68:71], v[186:189]
	s_nop 2
	ds_read_b64_tr_b16 v[186:187], v80 offset:224
	ds_read_b64_tr_b16 v[188:189], v80 offset:4832
	v_cvt_pk_bf16_f32 v60, v60, v61
	v_cvt_pk_bf16_f32 v61, v62, v63
	v_cvt_pk_bf16_f32 v62, v64, v65
	v_cndmask_b32_e64 v64, v88, v89, s[14:15]
	v_add_u32_e32 v80, v172, v64
	s_waitcnt lgkmcnt(2)
	v_mfma_f32_16x16x32_bf16 v[182:185], v[182:185], v[68:71], v[190:193]
	v_cvt_pk_bf16_f32 v63, v66, v67
	s_waitcnt lgkmcnt(0)
	v_mfma_f32_16x16x32_bf16 v[48:51], v[186:189], v[68:71], v[48:51]
	ds_read_b64_tr_b16 v[66:67], v80 offset:4608
	ds_read_b64_tr_b16 v[64:65], v80
	ds_read_b64_tr_b16 v[68:69], v80 offset:32
	ds_read_b64_tr_b16 v[70:71], v80 offset:4640
	s_waitcnt lgkmcnt(2)
	v_mfma_f32_16x16x32_bf16 v[64:67], v[64:67], v[60:63], v[72:75]
	s_nop 2
	ds_read_b64_tr_b16 v[72:73], v80 offset:64
	ds_read_b64_tr_b16 v[74:75], v80 offset:4672
	s_waitcnt lgkmcnt(0)
	v_mfma_f32_16x16x32_bf16 v[90:93], v[72:75], v[60:63], v[90:93]
	ds_read_b64_tr_b16 v[72:73], v80 offset:96
	ds_read_b64_tr_b16 v[74:75], v80 offset:4704
	s_waitcnt lgkmcnt(0)
	v_mfma_f32_16x16x32_bf16 v[94:97], v[72:75], v[60:63], v[94:97]
	ds_read_b64_tr_b16 v[72:73], v80 offset:128
	ds_read_b64_tr_b16 v[74:75], v80 offset:4736
	s_waitcnt lgkmcnt(0)
	v_mfma_f32_16x16x32_bf16 v[174:177], v[72:75], v[60:63], v[174:177]
	ds_read_b64_tr_b16 v[72:73], v80 offset:160
	ds_read_b64_tr_b16 v[74:75], v80 offset:4768
	s_waitcnt lgkmcnt(0)
	v_mfma_f32_16x16x32_bf16 v[178:181], v[72:75], v[60:63], v[178:181]
	ds_read_b64_tr_b16 v[72:73], v80 offset:192
	ds_read_b64_tr_b16 v[74:75], v80 offset:4800
	s_waitcnt lgkmcnt(0)
; #define LAS __attribute__((address_space(3)))
; __device__ __forceinline__ unsigned cvt_pk_bf16(float lo, float hi) { unsigned r; asm volatile("v_cvt_pk_bf16_f32 %0, %1, %2" : "=v"(r) : "v"(lo), "v"(hi)); return r; }
; __device__ __forceinline__ void attn_phase(const Params& p, LAS unsigned char* lds, int l, int mode) {
;     ...
;                     const s16x4 hi = __builtin_bit_cast(s16x4, __builtin_amdgcn_ds_read_tr16_b64_v4i16((LAS s16x4*)(vb + 16 * 288 + db * 32)));
;                     const bf16x8 vf = __builtin_shufflevector(lo, hi, 0, 1, 2, 3, 4, 5, 6, 7);
;                     oacc[db] = __builtin_amdgcn_mfma_f32_16x16x32_bf16(vf, pf, oacc[db], 0, 0, 0);
;                 }
;             }
;             const float inv = 1.0f / lsum, lse0 = mx + __builtin_amdgcn_logf(lsum);
;             if (mode == 0) {
;                 bf16_t* op = opart + ((size_t)(cur.br - 1) * T_TOK + qtok) * 1024 + h * 128 + 4 * g;
; #pragma unroll
;                 for (int db = 0; db < 8; ++db) { const f32x4 o = oacc[db] * inv; u32x2 w; w.x = cvt_pk_bf16(o[0], o[1]); w.y = cvt_pk_bf16(o[2], o[3]); *(u32x2*)(op + 16 * db) = w; }
;                 if (g == 0) lse[((size_t)(cur.br - 1) * T_TOK + qtok) * 8 + h] = lse0;
	v_mfma_f32_16x16x32_bf16 v[182:185], v[72:75], v[60:63], v[182:185]
	ds_read_b64_tr_b16 v[72:73], v80 offset:224
	ds_read_b64_tr_b16 v[74:75], v80 offset:4832
	v_cvt_pk_bf16_f32 v186, v52, v53
	v_cndmask_b32_e64 v52, v88, v89, s[16:17]
	v_add_u32_e32 v80, v173, v52
	v_cvt_pk_bf16_f32 v187, v54, v55
	v_cvt_pk_bf16_f32 v188, v56, v57
	v_cvt_pk_bf16_f32 v189, v58, v59
	ds_read_b64_tr_b16 v[54:55], v80 offset:4608
	ds_read_b64_tr_b16 v[52:53], v80
	ds_read_b64_tr_b16 v[56:57], v80 offset:32
	ds_read_b64_tr_b16 v[58:59], v80 offset:4640
	v_mfma_f32_16x16x32_bf16 v[68:71], v[68:71], v[60:63], v[76:79]
	s_waitcnt lgkmcnt(2)
	v_mfma_f32_16x16x32_bf16 v[76:79], v[52:55], v[186:189], v[64:67]
	ds_read_b64_tr_b16 v[52:53], v80 offset:64
	ds_read_b64_tr_b16 v[54:55], v80 offset:4672
	v_mfma_f32_16x16x32_bf16 v[48:51], v[72:75], v[60:63], v[48:51]
	s_waitcnt lgkmcnt(2)
	v_mfma_f32_16x16x32_bf16 v[72:75], v[56:59], v[186:189], v[68:71]
	s_waitcnt lgkmcnt(0)
	v_mfma_f32_16x16x32_bf16 v[68:71], v[52:55], v[186:189], v[90:93]
	ds_read_b64_tr_b16 v[52:53], v80 offset:96
	ds_read_b64_tr_b16 v[54:55], v80 offset:4704
	s_waitcnt lgkmcnt(0)
	v_mfma_f32_16x16x32_bf16 v[64:67], v[52:55], v[186:189], v[94:97]
	ds_read_b64_tr_b16 v[52:53], v80 offset:128
	ds_read_b64_tr_b16 v[54:55], v80 offset:4736
	s_waitcnt lgkmcnt(0)
	v_mfma_f32_16x16x32_bf16 v[60:63], v[52:55], v[186:189], v[174:177]
	ds_read_b64_tr_b16 v[52:53], v80 offset:160
	ds_read_b64_tr_b16 v[54:55], v80 offset:4768
	s_waitcnt lgkmcnt(0)
	v_mfma_f32_16x16x32_bf16 v[56:59], v[52:55], v[186:189], v[178:181]
	ds_read_b64_tr_b16 v[52:53], v80 offset:192
	ds_read_b64_tr_b16 v[54:55], v80 offset:4800
	ds_read_b64_tr_b16 v[88:89], v80 offset:224
	ds_read_b64_tr_b16 v[90:91], v80 offset:4832
	v_div_scale_f32 v80, s[26:27], v86, v86, 1.0
	v_rcp_f32_e32 v82, v80
	s_waitcnt lgkmcnt(0)
	v_mfma_f32_16x16x32_bf16 v[48:51], v[88:91], v[186:189], v[48:51]
	v_fma_f32 v83, -v80, v82, 1.0
	v_fmac_f32_e32 v82, v83, v82
	v_div_scale_f32 v83, vcc, 1.0, v86, 1.0
	v_mul_f32_e32 v87, v83, v82
	v_fma_f32 v88, -v80, v87, v83
	v_fmac_f32_e32 v87, v88, v82
	v_fma_f32 v80, -v80, v87, v83
	v_mfma_f32_16x16x32_bf16 v[52:55], v[52:55], v[186:189], v[182:185]
	v_div_fmas_f32 v80, v80, v82, v87
	v_lshl_add_u64 v[82:83], s[18:19], 0, v[84:85]
	v_readlane_b32 s18, v252, 61
	v_lshlrev_b64 v[84:85], 11, v[82:83]
	v_readlane_b32 s19, v252, 62
	v_div_fixup_f32 v80, v80, v86, 1.0
	v_pk_mul_f32 v[76:77], v[80:81], v[76:77] op_sel_hi:[0,1]
	v_lshl_add_u64 v[84:85], s[18:19], 0, v[84:85]
	v_lshl_add_u64 v[84:85], v[84:85], 0, s[52:53]
	v_lshl_add_u64 v[84:85], v[84:85], 0, v[152:153]
	v_pk_mul_f32 v[72:73], v[80:81], v[72:73] op_sel_hi:[0,1]
	v_pk_mul_f32 v[68:69], v[80:81], v[68:69] op_sel_hi:[0,1]
	v_pk_mul_f32 v[64:65], v[80:81], v[64:65] op_sel_hi:[0,1]
	v_pk_mul_f32 v[60:61], v[80:81], v[60:61] op_sel_hi:[0,1]
	v_pk_mul_f32 v[56:57], v[80:81], v[56:57] op_sel_hi:[0,1]
	v_pk_mul_f32 v[52:53], v[80:81], v[52:53] op_sel_hi:[0,1]
	v_pk_mul_f32 v[48:49], v[80:81], v[48:49] op_sel_hi:[0,1]
	v_pk_mul_f32 v[78:79], v[80:81], v[78:79] op_sel_hi:[0,1]
	v_cvt_pk_bf16_f32 v76, v76, v77
	v_cvt_pk_bf16_f32 v77, v78, v79
	global_store_dwordx2 v[84:85], v[76:77], off nt
	v_pk_mul_f32 v[74:75], v[80:81], v[74:75] op_sel_hi:[0,1]
	v_cvt_pk_bf16_f32 v72, v72, v73
	v_cvt_pk_bf16_f32 v73, v74, v75
	global_store_dwordx2 v[84:85], v[72:73], off offset:32 nt
	v_pk_mul_f32 v[70:71], v[80:81], v[70:71] op_sel_hi:[0,1]
	v_cvt_pk_bf16_f32 v68, v68, v69
	v_cvt_pk_bf16_f32 v69, v70, v71
	global_store_dwordx2 v[84:85], v[68:69], off offset:64 nt
	v_pk_mul_f32 v[66:67], v[80:81], v[66:67] op_sel_hi:[0,1]
	v_cvt_pk_bf16_f32 v64, v64, v65
	v_cvt_pk_bf16_f32 v65, v66, v67
	global_store_dwordx2 v[84:85], v[64:65], off offset:96 nt
	v_pk_mul_f32 v[62:63], v[80:81], v[62:63] op_sel_hi:[0,1]
	v_cvt_pk_bf16_f32 v60, v60, v61
	v_cvt_pk_bf16_f32 v61, v62, v63
	global_store_dwordx2 v[84:85], v[60:61], off offset:128 nt
	v_pk_mul_f32 v[58:59], v[80:81], v[58:59] op_sel_hi:[0,1]
	v_cvt_pk_bf16_f32 v56, v56, v57
	v_cvt_pk_bf16_f32 v57, v58, v59
	global_store_dwordx2 v[84:85], v[56:57], off offset:160 nt
	v_pk_mul_f32 v[54:55], v[80:81], v[54:55] op_sel_hi:[0,1]
	v_cvt_pk_bf16_f32 v52, v52, v53
	v_cvt_pk_bf16_f32 v53, v54, v55
	global_store_dwordx2 v[84:85], v[52:53], off offset:192 nt
	v_pk_mul_f32 v[50:51], v[80:81], v[50:51] op_sel_hi:[0,1]
	v_cvt_pk_bf16_f32 v48, v48, v49
	v_cvt_pk_bf16_f32 v49, v50, v51
	global_store_dwordx2 v[84:85], v[48:49], off offset:224 nt
	s_and_saveexec_b64 s[18:19], s[40:41]
	s_cbranch_execz .LBB0_303
	v_log_f32_e32 v50, v86
	v_readlane_b32 s20, v252, 63
	v_lshlrev_b64 v[48:49], 5, v[82:83]
	v_readlane_b32 s21, v253, 0
	s_mov_b32 s13, s53
	v_add_f32_e32 v50, v81, v50
	v_lshl_add_u64 v[48:49], s[20:21], 0, v[48:49]
	v_lshl_add_u64 v[48:49], s[12:13], 2, v[48:49]
	global_store_dword v[48:49], v50, off nt
	s_branch .LBB0_303
